# E27: prompt-FoX epilogue stores widened dwordx2->dwordx4 via v_permlane32_swap (guide 7.3); on E23
# speedup vs baseline: 1.0039x; 1.0039x over previous
.LBB0_1400:
	ds_bpermute_b32 v2, v177, v192
	v_cmp_gt_i32_e32 vcc, s12, v146
	s_and_saveexec_b64 s[14:15], vcc
	s_xor_b64 s[18:19], exec, s[14:15]
	s_cbranch_execz .LBB0_1402
	s_waitcnt lgkmcnt(0)
	v_add_f32_e32 v2, v192, v2
	v_div_scale_f32 v4, s[16:17], v2, v2, 1.0
	v_rcp_f32_e32 v5, v4
	s_lshl_b64 s[14:15], s[60:61], 11
	v_readlane_b32 s13, v244, 42
	s_add_u32 s13, s13, s14
	v_fma_f32 v6, -v4, v5, 1.0
	v_fmac_f32_e32 v5, v6, v5
	v_div_scale_f32 v6, vcc, 1.0, v2, 1.0
	v_mul_f32_e32 v7, v6, v5
	v_fma_f32 v8, -v4, v7, v6
	v_readlane_b32 s14, v244, 43
	v_fmac_f32_e32 v7, v8, v5
	s_addc_u32 s15, s14, s15
	v_fma_f32 v4, -v4, v7, v6
	s_add_u32 s14, s13, s96
	v_div_fmas_f32 v4, v4, v5, v7
	v_ashrrev_i32_e32 v147, 31, v146
	s_addc_u32 s15, s15, s97
	v_div_fixup_f32 v4, v4, v2, 1.0
	v_lshlrev_b64 v[6:7], 11, v[146:147]
	v_lshl_add_u64 v[6:7], s[14:15], 0, v[6:7]
	v_lshlrev_b32_e32 v2, 2, v216
	v_lshl_add_u64 v[6:7], v[6:7], 0, v[2:3]
	v_pk_mul_f32 v[60:61], v[34:35], v[4:5] op_sel_hi:[1,0]
	v_pk_mul_f32 v[62:63], v[36:37], v[4:5] op_sel_hi:[1,0]
	v_pk_mul_f32 v[64:65], v[38:39], v[4:5] op_sel_hi:[1,0]
	v_pk_mul_f32 v[66:67], v[40:41], v[4:5] op_sel_hi:[1,0]
	v_cvt_pk_bf16_f32 v8, v60, v61
	v_cvt_pk_bf16_f32 v9, v62, v63
	v_cvt_pk_bf16_f32 v10, v64, v65
	v_cvt_pk_bf16_f32 v11, v66, v67
	s_nop 1
	v_permlane32_swap_b32_e32 v8, v10
	v_permlane32_swap_b32_e32 v9, v11
	global_store_dwordx4 v[6:7], v[8:11], off
	v_pk_mul_f32 v[60:61], v[42:43], v[4:5] op_sel_hi:[1,0]
	v_pk_mul_f32 v[62:63], v[44:45], v[4:5] op_sel_hi:[1,0]
	v_pk_mul_f32 v[64:65], v[46:47], v[4:5] op_sel_hi:[1,0]
	v_pk_mul_f32 v[66:67], v[48:49], v[4:5] op_sel_hi:[1,0]
	v_cvt_pk_bf16_f32 v50, v60, v61
	v_cvt_pk_bf16_f32 v51, v62, v63
	v_cvt_pk_bf16_f32 v52, v64, v65
	v_cvt_pk_bf16_f32 v53, v66, v67
	s_nop 1
	v_permlane32_swap_b32_e32 v50, v52
	v_permlane32_swap_b32_e32 v51, v53
	global_store_dwordx4 v[6:7], v[50:53], off offset:32
	v_pk_mul_f32 v[60:61], v[18:19], v[4:5] op_sel_hi:[1,0]
	v_pk_mul_f32 v[62:63], v[20:21], v[4:5] op_sel_hi:[1,0]
	v_pk_mul_f32 v[64:65], v[22:23], v[4:5] op_sel_hi:[1,0]
	v_pk_mul_f32 v[66:67], v[24:25], v[4:5] op_sel_hi:[1,0]
	v_cvt_pk_bf16_f32 v8, v60, v61
	v_cvt_pk_bf16_f32 v9, v62, v63
	v_cvt_pk_bf16_f32 v10, v64, v65
	v_cvt_pk_bf16_f32 v11, v66, v67
	s_nop 1
	v_permlane32_swap_b32_e32 v8, v10
	v_permlane32_swap_b32_e32 v9, v11
	global_store_dwordx4 v[6:7], v[8:11], off offset:64
	v_pk_mul_f32 v[60:61], v[26:27], v[4:5] op_sel_hi:[1,0]
	v_pk_mul_f32 v[62:63], v[28:29], v[4:5] op_sel_hi:[1,0]
	v_pk_mul_f32 v[64:65], v[30:31], v[4:5] op_sel_hi:[1,0]
	v_pk_mul_f32 v[66:67], v[32:33], v[4:5] op_sel_hi:[1,0]
	v_cvt_pk_bf16_f32 v50, v60, v61
	v_cvt_pk_bf16_f32 v51, v62, v63
	v_cvt_pk_bf16_f32 v52, v64, v65
	v_cvt_pk_bf16_f32 v53, v66, v67
	s_nop 1
	v_permlane32_swap_b32_e32 v50, v52
	v_permlane32_swap_b32_e32 v51, v53
	global_store_dwordx4 v[6:7], v[50:53], off offset:96
